# same as previous plus a defensive counted vmcnt(8) before the P10 epilogue reads its prefetched row sums
# baseline (speedup 1.0000x reference)
; template <int NP> DI float row_rstd(const float* P, int row, float invn) {
;     if (NP == 0) return 1.0f;
;     return __builtin_amdgcn_rsqf(P[row] * invn + EPS);
; }
; DI void atomic_addf(float* p, float v) { __builtin_amdgcn_global_atomic_fadd_f32((__attribute__((address_space(1))) float*)p, v); }
; DI float quad_sum(float s) { s += __shfl_xor(s, 16); s += __shfl_xor(s, 32); return s; }
;     DI void operator()(const f32x4 (&acc)[2][2][4][2], const Unit& u, int wr, int wc, int fr, int fq) const {
;         const int row0 = u.pm * 256 + wr * 64 + fr, col0 = u.pn * 128 + wc * 32 + 8 * fq;
; #pragma unroll
;         for (int ai = 0; ai < 2; ++ai)
; #pragma unroll
;             for (int m = 0; m < 4; ++m) {
;                 const int row = row0 + ai * 128 + m * 16; const float rs = row_rstd<NP>(P, row, 1.0f / 1024.0f);
.LBB0_1826:
	v_lshl_add_u32 v144, s24, 8, v152
	v_ashrrev_i32_e32 v145, 31, v144
	v_or_b32_e32 v162, 16, v144
	v_ashrrev_i32_e32 v163, 31, v162
	v_lshl_or_b32 v148, s55, 7, v154
	v_mov_b64_e32 v[146:147], s[6:7]
	v_ashrrev_i32_e32 v149, 31, v148
	v_mad_i64_i32 v[160:161], s[12:13], v144, s54, v[146:147]
	v_lshlrev_b64 v[148:149], 1, v[148:149]
	v_lshl_add_u64 v[160:161], v[160:161], 0, v[148:149]
	v_readlane_b32 s56, v249, 1
	v_readlane_b32 s68, v249, 13
	v_readlane_b32 s69, v249, 14
	v_readlane_b32 s70, v249, 15
	v_readlane_b32 s71, v249, 16
	s_mov_b64 s[28:29], s[68:69]
	s_andn2_b64 vcc, exec, s[2:3]
	s_mov_b64 s[2:3], -1
	s_mov_b64 s[30:31], s[70:71]
	v_readlane_b32 s57, v249, 2
	v_readlane_b32 s58, v249, 3
	v_readlane_b32 s59, v249, 4
	v_readlane_b32 s60, v249, 5
	v_readlane_b32 s61, v249, 6
	v_readlane_b32 s62, v249, 7
	v_readlane_b32 s63, v249, 8
	v_readlane_b32 s64, v249, 9
	v_readlane_b32 s65, v249, 10
	v_readlane_b32 s66, v249, 11
	v_readlane_b32 s67, v249, 12
	s_waitcnt vmcnt(8)
	v_fmamk_f32 v238, v230, 0x3a800000, v158
	v_fmamk_f32 v239, v231, 0x3a800000, v158
	v_fmamk_f32 v240, v232, 0x3a800000, v158
	v_fmamk_f32 v241, v233, 0x3a800000, v158
	v_fmamk_f32 v242, v234, 0x3a800000, v158
	v_fmamk_f32 v243, v235, 0x3a800000, v158
	v_fmamk_f32 v244, v236, 0x3a800000, v158
	v_fmamk_f32 v245, v237, 0x3a800000, v158
	s_cbranch_vccnz .Lp10_nopf
	v_lshl_add_u32 v228, s18, 8, v152
	v_mov_b32_e32 v229, 0
	v_lshl_add_u64 v[228:229], v[228:229], 2, s[8:9]
	global_load_dword v230, v[228:229], off
	global_load_dword v231, v[228:229], off offset:64
	global_load_dword v232, v[228:229], off offset:128
	global_load_dword v233, v[228:229], off offset:192
	global_load_dword v234, v[228:229], off offset:512
	global_load_dword v235, v[228:229], off offset:576
	global_load_dword v236, v[228:229], off offset:640
	global_load_dword v237, v[228:229], off offset:704
